# seams: all waiters poll the cross-XCD arrival counter (target nXCD*(round+1)) instead of the release generation; TOPGEN atomic removed
# speedup vs baseline: 1.0005x; 1.0005x over previous
.LBB0_147:
	s_or_b64 exec, exec, s[16:17]
	v_cvt_f32_u32_e32 v4, v2
	s_waitcnt vmcnt(0)
	v_readfirstlane_b32 s3, v3
	v_sub_u32_e32 v3, 0, v2
	v_rcp_iflag_f32_e32 v4, v4
	v_add_u32_e32 v5, s3, v1
	v_mul_f32_e32 v4, 0x4f7ffffe, v4
	v_cvt_u32_f32_e32 v4, v4
	v_mul_lo_u32 v1, v3, v4
	v_mul_hi_u32 v1, v4, v1
	v_add_u32_e32 v1, v4, v1
	v_mul_hi_u32 v1, v5, v1
	v_mul_lo_u32 v3, v1, v2
	v_sub_u32_e32 v3, v5, v3
	v_add_u32_e32 v4, 1, v1
	v_cmp_ge_u32_e32 vcc, v3, v2
	s_nop 1
	v_cndmask_b32_e32 v1, v1, v4, vcc
	v_sub_u32_e32 v4, v3, v2
	v_cndmask_b32_e32 v3, v3, v4, vcc
	v_add_u32_e32 v4, 1, v1
	v_cmp_ge_u32_e32 vcc, v3, v2
	v_add_u32_e32 v3, 1, v5
	s_nop 0
	v_cndmask_b32_e32 v1, v1, v4, vcc
	v_mul_lo_u32 v4, v2, v1
	v_add_u32_e32 v2, v4, v2
	v_cmp_ne_u32_e32 vcc, v3, v2
	s_and_saveexec_b64 s[8:9], vcc
	s_xor_b64 s[8:9], exec, s[8:9]
	s_cbranch_execz .LBB0_161
	s_waitcnt lgkmcnt(0)
	v_add_u32_e32 v1, 1, v1
	v_mul_lo_u32 v1, v1, v0
	v_mov_b32_e32 v0, 0x3000
	global_load_dword v0, v0, s[80:81] offset:1024 sc1
	s_add_u32 s20, s80, 0x3400
	s_addc_u32 s21, s81, 0
	s_waitcnt vmcnt(0)
	v_cmp_lt_u32_e32 vcc, v0, v1
	s_and_saveexec_b64 s[16:17], vcc
	s_cbranch_execz .LBB0_160
	s_add_u32 s18, s88, 0x10200
	s_addc_u32 s19, s89, 0
	s_mov_b32 s3, 1
	s_mov_b64 s[22:23], 0
	v_mov_b32_e32 v0, 0
	s_branch .LBB0_151

.LBB0_155:
	global_load_dword v2, v0, s[20:21] sc1
	s_add_i32 s3, s3, 1
	s_mov_b64 s[28:29], -1
	s_waitcnt vmcnt(0)
	v_cmp_ge_u32_e32 vcc, v2, v1
	s_orn2_b64 s[26:27], vcc, exec
	s_branch .LBB0_150

.LBB0_164:
	s_or_b64 exec, exec, s[16:17]
	v_cvt_f32_u32_e32 v3, v0
	s_waitcnt vmcnt(0)
	v_readfirstlane_b32 s3, v2
	s_add_u32 s16, s88, 0x13500
	s_addc_u32 s17, s89, 0
	v_rcp_iflag_f32_e32 v3, v3
	v_add_u32_e32 v1, s3, v1
	v_add_u32_e32 v4, 1, v1
	s_mov_b64 s[18:19], -1
	v_mul_f32_e32 v2, 0x4f7ffffe, v3
	v_cvt_u32_f32_e32 v2, v2
	v_sub_u32_e32 v3, 0, v0
	v_mul_lo_u32 v3, v3, v2
	v_mul_hi_u32 v3, v2, v3
	v_add_u32_e32 v2, v2, v3
	v_mul_hi_u32 v2, v1, v2
	v_mul_lo_u32 v3, v2, v0
	v_sub_u32_e32 v1, v1, v3
	v_add_u32_e32 v5, 1, v2
	v_cmp_ge_u32_e32 vcc, v1, v0
	v_sub_u32_e32 v3, v1, v0
	s_nop 0
	v_cndmask_b32_e32 v2, v2, v5, vcc
	v_cndmask_b32_e32 v1, v1, v3, vcc
	v_add_u32_e32 v3, 1, v2
	v_cmp_ge_u32_e32 vcc, v1, v0
	s_nop 1
	v_cndmask_b32_e32 v2, v2, v3, vcc
	v_mul_lo_u32 v1, v0, v2
	v_add_u32_e32 v0, v1, v0
	v_cmp_ne_u32_e32 vcc, v4, v0
	v_mov_b32_e32 v5, v0
	v_mov_b64_e32 v[0:1], s[16:17]
	s_and_saveexec_b64 s[8:9], vcc
	s_cbranch_execz .LBB0_176
	v_mov_b32_e32 v0, 0
	global_load_dword v1, v0, s[16:17] offset:-256 sc1
	s_mov_b64 s[22:23], 0
	s_waitcnt vmcnt(0)
	v_cmp_lt_u32_e32 vcc, v1, v5
	s_and_saveexec_b64 s[20:21], vcc
	s_cbranch_execz .LBB0_175
	s_add_u32 s18, s88, 0x10200
	s_addc_u32 s19, s89, 0
	s_mov_b32 s3, 1
	s_branch .LBB0_168

.LBB0_172:
	global_load_dword v1, v0, s[16:17] offset:-256 sc1
	s_add_i32 s3, s3, 1
	s_mov_b64 s[26:27], -1
	s_waitcnt vmcnt(0)
	v_cmp_ge_u32_e32 vcc, v1, v5
	s_orn2_b64 s[30:31], vcc, exec
	s_branch .LBB0_167

.LBB0_176:
	s_or_b64 exec, exec, s[8:9]
	s_and_saveexec_b64 s[8:9], s[18:19]
	s_cbranch_execz .LBB0_178
	v_mov_b32_e32 v2, 1
.LBB0_178:
	s_or_b64 exec, exec, s[8:9]
	s_mov_b64 s[8:9], exec
	v_mbcnt_lo_u32_b32 v0, s8, 0
	v_mbcnt_hi_u32_b32 v0, s9, v0
	v_cmp_eq_u32_e32 vcc, 0, v0
	s_waitcnt vmcnt(0)
	buffer_inv sc1
	s_and_saveexec_b64 s[16:17], vcc
	s_cbranch_execz .LBB0_180
	s_bcnt1_i32_b64 s3, s[8:9]
	v_mov_b32_e32 v0, 0x2000
	v_mov_b32_e32 v1, s3

.LBB0_279:
	s_or_b64 exec, exec, s[10:11]
	v_cvt_f32_u32_e32 v4, v2
	s_waitcnt vmcnt(0)
	v_readfirstlane_b32 s3, v3
	v_sub_u32_e32 v3, 0, v2
	v_rcp_iflag_f32_e32 v4, v4
	v_add_u32_e32 v5, s3, v1
	v_mul_f32_e32 v4, 0x4f7ffffe, v4
	v_cvt_u32_f32_e32 v4, v4
	v_mul_lo_u32 v1, v3, v4
	v_mul_hi_u32 v1, v4, v1
	v_add_u32_e32 v1, v4, v1
	v_mul_hi_u32 v1, v5, v1
	v_mul_lo_u32 v3, v1, v2
	v_sub_u32_e32 v3, v5, v3
	v_add_u32_e32 v4, 1, v1
	v_cmp_ge_u32_e32 vcc, v3, v2
	s_nop 1
	v_cndmask_b32_e32 v1, v1, v4, vcc
	v_sub_u32_e32 v4, v3, v2
	v_cndmask_b32_e32 v3, v3, v4, vcc
	v_add_u32_e32 v4, 1, v1
	v_cmp_ge_u32_e32 vcc, v3, v2
	v_add_u32_e32 v3, 1, v5
	s_nop 0
	v_cndmask_b32_e32 v1, v1, v4, vcc
	v_mul_lo_u32 v4, v2, v1
	v_add_u32_e32 v2, v4, v2
	v_cmp_ne_u32_e32 vcc, v3, v2
	s_and_saveexec_b64 s[8:9], vcc
	s_xor_b64 s[8:9], exec, s[8:9]
	s_cbranch_execz .LBB0_293
	s_waitcnt lgkmcnt(0)
	v_add_u32_e32 v1, 1, v1
	v_mul_lo_u32 v1, v1, v0
	v_mov_b32_e32 v0, 0x3000
	global_load_dword v0, v0, s[80:81] offset:1024 sc1
	s_add_u32 s16, s80, 0x3400
	s_addc_u32 s17, s81, 0
	s_waitcnt vmcnt(0)
	v_cmp_lt_u32_e32 vcc, v0, v1
	s_and_saveexec_b64 s[10:11], vcc
	s_cbranch_execz .LBB0_292
	s_add_u32 s12, s88, 0x10200
	s_addc_u32 s13, s89, 0
	s_mov_b32 s3, 1
	s_mov_b64 s[18:19], 0
	v_mov_b32_e32 v0, 0
	s_branch .LBB0_283

.LBB0_287:
	global_load_dword v2, v0, s[16:17] sc1
	s_add_i32 s3, s3, 1
	s_mov_b64 s[24:25], -1
	s_waitcnt vmcnt(0)
	v_cmp_ge_u32_e32 vcc, v2, v1
	s_orn2_b64 s[22:23], vcc, exec
	s_branch .LBB0_282

.LBB0_296:
	s_or_b64 exec, exec, s[10:11]
	v_cvt_f32_u32_e32 v3, v0
	s_waitcnt vmcnt(0)
	v_readfirstlane_b32 s3, v2
	s_add_u32 s10, s88, 0x13500
	s_addc_u32 s11, s89, 0
	v_rcp_iflag_f32_e32 v3, v3
	v_add_u32_e32 v1, s3, v1
	v_add_u32_e32 v4, 1, v1
	s_mov_b64 s[12:13], -1
	v_mul_f32_e32 v2, 0x4f7ffffe, v3
	v_cvt_u32_f32_e32 v2, v2
	v_sub_u32_e32 v3, 0, v0
	v_mul_lo_u32 v3, v3, v2
	v_mul_hi_u32 v3, v2, v3
	v_add_u32_e32 v2, v2, v3
	v_mul_hi_u32 v2, v1, v2
	v_mul_lo_u32 v3, v2, v0
	v_sub_u32_e32 v1, v1, v3
	v_add_u32_e32 v5, 1, v2
	v_cmp_ge_u32_e32 vcc, v1, v0
	v_sub_u32_e32 v3, v1, v0
	s_nop 0
	v_cndmask_b32_e32 v2, v2, v5, vcc
	v_cndmask_b32_e32 v1, v1, v3, vcc
	v_add_u32_e32 v3, 1, v2
	v_cmp_ge_u32_e32 vcc, v1, v0
	s_nop 1
	v_cndmask_b32_e32 v2, v2, v3, vcc
	v_mul_lo_u32 v1, v0, v2
	v_add_u32_e32 v0, v1, v0
	v_cmp_ne_u32_e32 vcc, v4, v0
	v_mov_b32_e32 v5, v0
	v_mov_b64_e32 v[0:1], s[10:11]
	s_and_saveexec_b64 s[8:9], vcc
	s_cbranch_execz .LBB0_308
	v_mov_b32_e32 v0, 0
	global_load_dword v1, v0, s[10:11] offset:-256 sc1
	s_mov_b64 s[18:19], 0
	s_waitcnt vmcnt(0)
	v_cmp_lt_u32_e32 vcc, v1, v5
	s_and_saveexec_b64 s[16:17], vcc
	s_cbranch_execz .LBB0_307
	s_add_u32 s12, s88, 0x10200
	s_addc_u32 s13, s89, 0
	s_mov_b32 s3, 1
	s_branch .LBB0_300

.LBB0_304:
	global_load_dword v1, v0, s[10:11] offset:-256 sc1
	s_add_i32 s3, s3, 1
	s_mov_b64 s[22:23], -1
	s_waitcnt vmcnt(0)
	v_cmp_ge_u32_e32 vcc, v1, v5
	s_orn2_b64 s[26:27], vcc, exec
	s_branch .LBB0_299

.LBB0_308:
	s_or_b64 exec, exec, s[8:9]
	s_and_saveexec_b64 s[8:9], s[12:13]
	s_cbranch_execz .LBB0_310
	v_mov_b32_e32 v2, 1
.LBB0_310:
	s_or_b64 exec, exec, s[8:9]
	s_mov_b64 s[8:9], exec
	v_mbcnt_lo_u32_b32 v0, s8, 0
	v_mbcnt_hi_u32_b32 v0, s9, v0
	v_cmp_eq_u32_e32 vcc, 0, v0
	s_waitcnt vmcnt(0)
	buffer_inv sc1
	s_and_saveexec_b64 s[10:11], vcc
	s_cbranch_execz .LBB0_312
	s_bcnt1_i32_b64 s3, s[8:9]
	v_mov_b32_e32 v0, 0x2000
	v_mov_b32_e32 v1, s3

.LBB0_449:
	s_or_b64 exec, exec, s[10:11]
	v_cvt_f32_u32_e32 v4, v2
	s_waitcnt vmcnt(0)
	v_readfirstlane_b32 s3, v3
	v_sub_u32_e32 v3, 0, v2
	v_rcp_iflag_f32_e32 v4, v4
	v_add_u32_e32 v5, s3, v1
	v_mul_f32_e32 v4, 0x4f7ffffe, v4
	v_cvt_u32_f32_e32 v4, v4
	v_mul_lo_u32 v1, v3, v4
	v_mul_hi_u32 v1, v4, v1
	v_add_u32_e32 v1, v4, v1
	v_mul_hi_u32 v1, v5, v1
	v_mul_lo_u32 v3, v1, v2
	v_sub_u32_e32 v3, v5, v3
	v_add_u32_e32 v4, 1, v1
	v_cmp_ge_u32_e32 vcc, v3, v2
	s_nop 1
	v_cndmask_b32_e32 v1, v1, v4, vcc
	v_sub_u32_e32 v4, v3, v2
	v_cndmask_b32_e32 v3, v3, v4, vcc
	v_add_u32_e32 v4, 1, v1
	v_cmp_ge_u32_e32 vcc, v3, v2
	v_add_u32_e32 v3, 1, v5
	s_nop 0
	v_cndmask_b32_e32 v1, v1, v4, vcc
	v_mul_lo_u32 v4, v2, v1
	v_add_u32_e32 v2, v4, v2
	v_cmp_ne_u32_e32 vcc, v3, v2
	s_and_saveexec_b64 s[8:9], vcc
	s_xor_b64 s[8:9], exec, s[8:9]
	s_cbranch_execz .LBB0_463
	s_waitcnt lgkmcnt(0)
	v_add_u32_e32 v1, 1, v1
	v_mul_lo_u32 v1, v1, v0
	v_mov_b32_e32 v0, 0x3000
	global_load_dword v0, v0, s[80:81] offset:1024 sc1
	s_add_u32 s14, s80, 0x3400
	s_addc_u32 s15, s81, 0
	s_waitcnt vmcnt(0)
	v_cmp_lt_u32_e32 vcc, v0, v1
	s_and_saveexec_b64 s[10:11], vcc
	s_cbranch_execz .LBB0_462
	s_add_u32 s12, s88, 0x10200
	s_addc_u32 s13, s89, 0
	s_mov_b32 s3, 1
	s_mov_b64 s[16:17], 0
	v_mov_b32_e32 v0, 0
	s_branch .LBB0_453

.LBB0_457:
	global_load_dword v2, v0, s[14:15] sc1
	s_add_i32 s3, s3, 1
	s_mov_b64 s[22:23], -1
	s_waitcnt vmcnt(0)
	v_cmp_ge_u32_e32 vcc, v2, v1
	s_orn2_b64 s[20:21], vcc, exec
	s_branch .LBB0_452

.LBB0_466:
	s_or_b64 exec, exec, s[10:11]
	v_cvt_f32_u32_e32 v3, v0
	s_waitcnt vmcnt(0)
	v_readfirstlane_b32 s3, v2
	s_add_u32 s10, s88, 0x13500
	s_addc_u32 s11, s89, 0
	v_rcp_iflag_f32_e32 v3, v3
	v_add_u32_e32 v1, s3, v1
	v_add_u32_e32 v4, 1, v1
	s_mov_b64 s[12:13], -1
	v_mul_f32_e32 v2, 0x4f7ffffe, v3
	v_cvt_u32_f32_e32 v2, v2
	v_sub_u32_e32 v3, 0, v0
	v_mul_lo_u32 v3, v3, v2
	v_mul_hi_u32 v3, v2, v3
	v_add_u32_e32 v2, v2, v3
	v_mul_hi_u32 v2, v1, v2
	v_mul_lo_u32 v3, v2, v0
	v_sub_u32_e32 v1, v1, v3
	v_add_u32_e32 v5, 1, v2
	v_cmp_ge_u32_e32 vcc, v1, v0
	v_sub_u32_e32 v3, v1, v0
	s_nop 0
	v_cndmask_b32_e32 v2, v2, v5, vcc
	v_cndmask_b32_e32 v1, v1, v3, vcc
	v_add_u32_e32 v3, 1, v2
	v_cmp_ge_u32_e32 vcc, v1, v0
	s_nop 1
	v_cndmask_b32_e32 v2, v2, v3, vcc
	v_mul_lo_u32 v1, v0, v2
	v_add_u32_e32 v0, v1, v0
	v_cmp_ne_u32_e32 vcc, v4, v0
	v_mov_b32_e32 v5, v0
	v_mov_b64_e32 v[0:1], s[10:11]
	s_and_saveexec_b64 s[8:9], vcc
	s_cbranch_execz .LBB0_478
	v_mov_b32_e32 v0, 0
	global_load_dword v1, v0, s[10:11] offset:-256 sc1
	s_mov_b64 s[16:17], 0
	s_waitcnt vmcnt(0)
	v_cmp_lt_u32_e32 vcc, v1, v5
	s_and_saveexec_b64 s[14:15], vcc
	s_cbranch_execz .LBB0_477
	s_add_u32 s12, s88, 0x10200
	s_addc_u32 s13, s89, 0
	s_mov_b32 s3, 1
	s_branch .LBB0_470

.LBB0_474:
	global_load_dword v1, v0, s[10:11] offset:-256 sc1
	s_add_i32 s3, s3, 1
	s_mov_b64 s[20:21], -1
	s_waitcnt vmcnt(0)
	v_cmp_ge_u32_e32 vcc, v1, v5
	s_orn2_b64 s[24:25], vcc, exec
	s_branch .LBB0_469

.LBB0_478:
	s_or_b64 exec, exec, s[8:9]
	s_and_saveexec_b64 s[8:9], s[12:13]
	s_cbranch_execz .LBB0_480
	v_mov_b32_e32 v2, 1
.LBB0_480:
	s_or_b64 exec, exec, s[8:9]
	s_mov_b64 s[8:9], exec
	v_mbcnt_lo_u32_b32 v0, s8, 0
	v_mbcnt_hi_u32_b32 v0, s9, v0
	v_cmp_eq_u32_e32 vcc, 0, v0
	s_waitcnt vmcnt(0)
	buffer_inv sc1
	s_and_saveexec_b64 s[10:11], vcc
	s_cbranch_execz .LBB0_482
	s_bcnt1_i32_b64 s3, s[8:9]
	v_mov_b32_e32 v0, 0x2000
	v_mov_b32_e32 v1, s3

.LBB0_559:
	s_or_b64 exec, exec, s[8:9]
	s_and_saveexec_b64 s[8:9], s[12:13]
	s_cbranch_execz .LBB0_561
	v_mov_b32_e32 v2, 1
.LBB0_561:
	s_or_b64 exec, exec, s[8:9]
	s_mov_b64 s[8:9], exec
	v_mbcnt_lo_u32_b32 v0, s8, 0
	v_mbcnt_hi_u32_b32 v0, s9, v0
	v_cmp_eq_u32_e32 vcc, 0, v0
	s_waitcnt vmcnt(0)
	buffer_inv sc1
	s_and_saveexec_b64 s[10:11], vcc
	s_cbranch_execz .LBB0_563
	s_bcnt1_i32_b64 s3, s[8:9]
	v_mov_b32_e32 v0, 0x2000
	v_mov_b32_e32 v1, s3

.LBB0_627:
	s_or_b64 exec, exec, s[8:9]
	v_cvt_f32_u32_e32 v4, v2
	s_waitcnt vmcnt(0)
	v_readfirstlane_b32 s3, v3
	v_sub_u32_e32 v3, 0, v2
	v_rcp_iflag_f32_e32 v4, v4
	v_add_u32_e32 v5, s3, v1
	v_mul_f32_e32 v4, 0x4f7ffffe, v4
	v_cvt_u32_f32_e32 v4, v4
	v_mul_lo_u32 v1, v3, v4
	v_mul_hi_u32 v1, v4, v1
	v_add_u32_e32 v1, v4, v1
	v_mul_hi_u32 v1, v5, v1
	v_mul_lo_u32 v3, v1, v2
	v_sub_u32_e32 v3, v5, v3
	v_add_u32_e32 v4, 1, v1
	v_cmp_ge_u32_e32 vcc, v3, v2
	s_nop 1
	v_cndmask_b32_e32 v1, v1, v4, vcc
	v_sub_u32_e32 v4, v3, v2
	v_cndmask_b32_e32 v3, v3, v4, vcc
	v_add_u32_e32 v4, 1, v1
	v_cmp_ge_u32_e32 vcc, v3, v2
	v_add_u32_e32 v3, 1, v5
	s_nop 0
	v_cndmask_b32_e32 v1, v1, v4, vcc
	v_mul_lo_u32 v4, v2, v1
	v_add_u32_e32 v2, v4, v2
	v_cmp_ne_u32_e32 vcc, v3, v2
	s_and_saveexec_b64 s[6:7], vcc
	s_xor_b64 s[6:7], exec, s[6:7]
	s_cbranch_execz .LBB0_641
	s_waitcnt lgkmcnt(0)
	v_add_u32_e32 v1, 1, v1
	v_mul_lo_u32 v1, v1, v0
	v_mov_b32_e32 v0, 0x3000
	global_load_dword v0, v0, s[80:81] offset:1024 sc1
	s_add_u32 s12, s80, 0x3400
	s_addc_u32 s13, s81, 0
	s_waitcnt vmcnt(0)
	v_cmp_lt_u32_e32 vcc, v0, v1
	s_and_saveexec_b64 s[8:9], vcc
	s_cbranch_execz .LBB0_640
	s_add_u32 s10, s88, 0x10200
	s_addc_u32 s11, s89, 0
	s_mov_b32 s3, 1
	s_mov_b64 s[16:17], 0
	v_mov_b32_e32 v0, 0
	s_branch .LBB0_631

.LBB0_635:
	global_load_dword v2, v0, s[12:13] sc1
	s_add_i32 s3, s3, 1
	s_mov_b64 s[22:23], -1
	s_waitcnt vmcnt(0)
	v_cmp_ge_u32_e32 vcc, v2, v1
	s_orn2_b64 s[20:21], vcc, exec
	s_branch .LBB0_630

.LBB0_644:
	s_or_b64 exec, exec, s[8:9]
	v_cvt_f32_u32_e32 v3, v0
	s_waitcnt vmcnt(0)
	v_readfirstlane_b32 s3, v2
	s_add_u32 s8, s88, 0x13500
	s_addc_u32 s9, s89, 0
	v_rcp_iflag_f32_e32 v3, v3
	v_add_u32_e32 v1, s3, v1
	v_add_u32_e32 v4, 1, v1
	s_mov_b64 s[10:11], -1
	v_mul_f32_e32 v2, 0x4f7ffffe, v3
	v_cvt_u32_f32_e32 v2, v2
	v_sub_u32_e32 v3, 0, v0
	v_mul_lo_u32 v3, v3, v2
	v_mul_hi_u32 v3, v2, v3
	v_add_u32_e32 v2, v2, v3
	v_mul_hi_u32 v2, v1, v2
	v_mul_lo_u32 v3, v2, v0
	v_sub_u32_e32 v1, v1, v3
	v_add_u32_e32 v5, 1, v2
	v_cmp_ge_u32_e32 vcc, v1, v0
	v_sub_u32_e32 v3, v1, v0
	s_nop 0
	v_cndmask_b32_e32 v2, v2, v5, vcc
	v_cndmask_b32_e32 v1, v1, v3, vcc
	v_add_u32_e32 v3, 1, v2
	v_cmp_ge_u32_e32 vcc, v1, v0
	s_nop 1
	v_cndmask_b32_e32 v2, v2, v3, vcc
	v_mul_lo_u32 v1, v0, v2
	v_add_u32_e32 v0, v1, v0
	v_cmp_ne_u32_e32 vcc, v4, v0
	v_mov_b32_e32 v5, v0
	v_mov_b64_e32 v[0:1], s[8:9]
	s_and_saveexec_b64 s[6:7], vcc
	s_cbranch_execz .LBB0_656
	v_mov_b32_e32 v0, 0
	global_load_dword v1, v0, s[8:9] offset:-256 sc1
	s_mov_b64 s[16:17], 0
	s_waitcnt vmcnt(0)
	v_cmp_lt_u32_e32 vcc, v1, v5
	s_and_saveexec_b64 s[12:13], vcc
	s_cbranch_execz .LBB0_655
	s_add_u32 s10, s88, 0x10200
	s_addc_u32 s11, s89, 0
	s_mov_b32 s3, 1
	s_branch .LBB0_648

.LBB0_652:
	global_load_dword v1, v0, s[8:9] offset:-256 sc1
	s_add_i32 s3, s3, 1
	s_mov_b64 s[20:21], -1
	s_waitcnt vmcnt(0)
	v_cmp_ge_u32_e32 vcc, v1, v5
	s_orn2_b64 s[24:25], vcc, exec
	s_branch .LBB0_647

.LBB0_656:
	s_or_b64 exec, exec, s[6:7]
	s_and_saveexec_b64 s[6:7], s[10:11]
	s_cbranch_execz .LBB0_658
	v_mov_b32_e32 v2, 1
.LBB0_658:
	s_or_b64 exec, exec, s[6:7]
	s_mov_b64 s[6:7], exec
	v_mbcnt_lo_u32_b32 v0, s6, 0
	v_mbcnt_hi_u32_b32 v0, s7, v0
	v_cmp_eq_u32_e32 vcc, 0, v0
	s_waitcnt vmcnt(0)
	buffer_inv sc1
	s_and_saveexec_b64 s[8:9], vcc
	s_cbranch_execz .LBB0_660
	s_bcnt1_i32_b64 s3, s[6:7]
	v_mov_b32_e32 v0, 0x2000
	v_mov_b32_e32 v1, s3

.LBB0_777:
	s_or_b64 exec, exec, s[6:7]
	s_and_saveexec_b64 s[6:7], s[10:11]
	s_cbranch_execz .LBB0_779
	v_mov_b32_e32 v2, 1
.LBB0_779:
	s_or_b64 exec, exec, s[6:7]
	s_mov_b64 s[6:7], exec
	v_mbcnt_lo_u32_b32 v0, s6, 0
	v_mbcnt_hi_u32_b32 v0, s7, v0
	v_cmp_eq_u32_e32 vcc, 0, v0
	s_waitcnt vmcnt(0)
	buffer_inv sc1
	s_and_saveexec_b64 s[8:9], vcc
	s_cbranch_execz .LBB0_781
	s_bcnt1_i32_b64 s3, s[6:7]
	v_mov_b32_e32 v0, 0x2000
	v_mov_b32_e32 v1, s3
